# attention epilogue: per-wave LDS transpose so the bf16 output goes out as 8 dwordx4 stores instead of 64 two-byte stores
# speedup vs baseline: 1.0098x; 1.0098x over previous
; __device__ __forceinline__ float shx(float v, int lane, int off) { return __builtin_bit_cast(float, __builtin_amdgcn_ds_bpermute((lane ^ off) << 2, __builtin_bit_cast(int, v))); }
; __device__ __forceinline__ void attn_unit(LAS unsigned char* lds, const bf16* Qh, const bf16* Kh, const bf16* VTh, const float* nrm, bf16* Y, const float* subln, float lam, int b, int h, int qb) {
;     ...
;     if (comp == 0) {
;         float ss[16];
; #pragma unroll
;         for (int r = 0; r < 16; ++r) { float a = 0.f;
; #pragma unroll
;             for (int blk = 0; blk < 4; ++blk) { const float d = o[blk][r] * rli[r] - cb[((wq * 4 + blk) * 16 + r) * 64 + lane]; o[blk][r] = d; a += d * d; }
;             ss[r] = a; }
; #pragma unroll
;         for (int r = 0; r < 16; ++r) {
; #pragma unroll
;             for (int off = 1; off < 32; off <<= 1) ss[r] += shx(ss[r], lane, off);
;             ss[r] = (1.0f - LAMBDA_INIT1) / sqrtf(ss[r] * (1.0f / 128.0f) + SUBLN_EPS); }
.LBB0_982:
	s_waitcnt lgkmcnt(0)
	s_barrier
	s_cmpk_gt_u32 s81, 0xff
	s_cbranch_scc1 .LBB0_876
	s_lshl_b32 s0, s81, 8
	s_and_b32 s0, s0, 0xc000
	s_add_i32 s0, s0, 0
	v_lshl_add_u32 v20, v203, 2, s0
	ds_read2st64_b32 v[28:29], v20 offset1:1
	ds_read2st64_b32 v[30:31], v20 offset0:16 offset1:17
	ds_read2st64_b32 v[34:35], v20 offset0:2 offset1:3
	ds_read2st64_b32 v[36:37], v20 offset0:4 offset1:5
	ds_read2st64_b32 v[38:39], v20 offset0:6 offset1:7
	ds_read2st64_b32 v[42:43], v20 offset0:18 offset1:19
	ds_read2st64_b32 v[44:45], v20 offset0:20 offset1:21
	ds_read2st64_b32 v[46:47], v20 offset0:22 offset1:23
	ds_read2st64_b32 v[32:33], v20 offset0:32 offset1:33
	ds_read2st64_b32 v[48:49], v20 offset0:34 offset1:35
	ds_read2st64_b32 v[50:51], v20 offset0:36 offset1:37
	ds_read2st64_b32 v[52:53], v20 offset0:38 offset1:39
	ds_read2st64_b32 v[56:57], v20 offset0:48 offset1:49
	ds_read2st64_b32 v[58:59], v20 offset0:50 offset1:51
	ds_read2st64_b32 v[60:61], v20 offset0:52 offset1:53
	ds_read2st64_b32 v[62:63], v20 offset0:54 offset1:55
	s_waitcnt lgkmcnt(14)
	v_fma_f32 v55, v112, v0, -v30
	v_fma_f32 v2, v96, v0, -v28
	v_mul_f32_e32 v54, v55, v55
	v_fmac_f32_e32 v54, v2, v2
	s_waitcnt lgkmcnt(7)
	v_fma_f32 v40, v80, v0, -v32
	v_fmac_f32_e32 v54, v40, v40
	s_waitcnt lgkmcnt(3)
	v_fma_f32 v32, v64, v0, -v56
	v_fmac_f32_e32 v54, v32, v32
	v_fma_f32 v4, v97, v1, -v29
	v_fma_f32 v56, v113, v1, -v31
	v_fma_f32 v41, v81, v1, -v33
	v_fma_f32 v33, v65, v1, -v57
	v_fma_f32 v12, v101, v13, -v37
	s_waitcnt lgkmcnt(1)
	v_fma_f32 v37, v69, v13, -v61
	v_fma_f32 v14, v102, v15, -v38
	v_fma_f32 v61, v118, v15, -v46
	v_fma_f32 v46, v86, v15, -v52
	s_waitcnt lgkmcnt(0)
	v_fma_f32 v38, v70, v15, -v62
	v_fma_f32 v16, v103, v18, -v39
	v_fma_f32 v62, v119, v18, -v47
	v_fma_f32 v47, v87, v18, -v53
	v_fma_f32 v39, v71, v18, -v63
	ds_read2st64_b32 v[0:1], v20 offset0:8 offset1:9
	ds_read2st64_b32 v[28:29], v20 offset0:24 offset1:25
	ds_read2st64_b32 v[30:31], v20 offset0:10 offset1:11
	ds_read2st64_b32 v[52:53], v20 offset0:12 offset1:13
	ds_read2st64_b32 v[70:71], v20 offset0:14 offset1:15
	s_waitcnt lgkmcnt(4)
	v_fma_f32 v18, v104, v5, -v0
	ds_bpermute_b32 v0, v207, v54
	v_fma_f32 v6, v98, v3, -v34
	v_fma_f32 v57, v114, v3, -v42
	v_fma_f32 v42, v82, v3, -v48
	v_fma_f32 v34, v66, v3, -v58
	s_waitcnt lgkmcnt(0)
	v_add_f32_e32 v0, v54, v0
	v_fma_f32 v8, v99, v7, -v35
	v_fma_f32 v58, v115, v7, -v43
	v_fma_f32 v43, v83, v7, -v49
	v_fma_f32 v35, v67, v7, -v59
	v_fma_f32 v10, v100, v11, -v36
	v_fma_f32 v59, v116, v11, -v44
	v_fma_f32 v44, v84, v11, -v50
	v_fma_f32 v36, v68, v11, -v60
	v_fma_f32 v60, v117, v13, -v45
	v_fma_f32 v45, v85, v13, -v51
	ds_read2st64_b32 v[50:51], v20 offset0:26 offset1:27
	ds_read2st64_b32 v[68:69], v20 offset0:28 offset1:29
	ds_read2st64_b32 v[82:83], v20 offset0:30 offset1:31
	ds_read2st64_b32 v[48:49], v20 offset0:40 offset1:41
	ds_read2st64_b32 v[66:67], v20 offset0:42 offset1:43
	ds_read2st64_b32 v[84:85], v20 offset0:44 offset1:45
	ds_read2st64_b32 v[86:87], v20 offset0:46 offset1:47
	ds_read2st64_b32 v[96:97], v20 offset0:56 offset1:57
	ds_read2st64_b32 v[98:99], v20 offset0:58 offset1:59
	ds_read2st64_b32 v[100:101], v20 offset0:60 offset1:61
	ds_read2st64_b32 v[102:103], v20 offset0:62 offset1:63
	v_fma_f32 v20, v105, v9, -v1
	ds_bpermute_b32 v1, v206, v0
	s_waitcnt lgkmcnt(8)
	v_fma_f32 v65, v89, v9, -v49
	s_waitcnt lgkmcnt(4)
	v_fma_f32 v49, v73, v9, -v97
	v_fma_f32 v73, v122, v23, -v50
	s_waitcnt lgkmcnt(3)
	v_fma_f32 v50, v74, v23, -v98
	s_waitcnt lgkmcnt(0)
	v_add_f32_e32 v0, v0, v1
	ds_bpermute_b32 v1, v205, v0
	v_fma_f32 v24, v107, v26, -v31
	v_fma_f32 v74, v123, v26, -v51
	v_fma_f32 v67, v91, v26, -v67
	v_fma_f32 v51, v75, v26, -v99
	s_waitcnt lgkmcnt(0)
	v_add_f32_e32 v0, v0, v1
	v_fma_f32 v26, v108, v21, -v52
	v_fma_f32 v75, v124, v21, -v68
	v_fma_f32 v68, v92, v21, -v84
	v_fma_f32 v52, v76, v21, -v100
	ds_bpermute_b32 v21, v204, v0
	v_mul_f32_e32 v64, v56, v56
	v_fmac_f32_e32 v64, v4, v4
	v_fmac_f32_e32 v64, v41, v41
	v_fmac_f32_e32 v64, v33, v33
	s_waitcnt lgkmcnt(0)
	v_add_f32_e32 v0, v0, v21
	ds_bpermute_b32 v21, v181, v0
	v_fma_f32 v63, v88, v5, -v48
	v_fma_f32 v48, v72, v5, -v96
	v_fma_f32 v72, v121, v9, -v29
	v_fma_f32 v22, v106, v23, -v30
	s_waitcnt lgkmcnt(0)
	v_add_f32_e32 v0, v0, v21
	v_fmamk_f32 v0, v0, 0x3c000000, v187
	v_mul_f32_e32 v21, 0x4f800000, v0
	v_cmp_gt_f32_e32 vcc, s85, v0
	v_fma_f32 v66, v90, v23, -v66
	ds_bpermute_b32 v29, v207, v64
	v_cndmask_b32_e32 v21, v0, v21, vcc
	v_sqrt_f32_e32 v23, v21
	v_fma_f32 v80, v120, v5, -v28
	v_fma_f32 v28, v109, v25, -v53
	v_fma_f32 v76, v125, v25, -v69
	v_fma_f32 v69, v93, v25, -v85
	v_fma_f32 v53, v77, v25, -v101
	v_add_u32_e32 v25, -1, v23
	v_fma_f32 v30, v110, v27, -v70
	v_fma_f32 v77, v126, v27, -v82
	v_fma_f32 v70, v94, v27, -v86
	v_fma_f32 v54, v78, v27, -v102
	v_fma_f32 v27, -v25, v23, v21
	s_waitcnt lgkmcnt(0)
	v_add_f32_e32 v29, v64, v29
	v_cmp_ge_f32_e64 s[10:11], 0, v27
	v_add_u32_e32 v27, 1, v23
	ds_bpermute_b32 v31, v206, v29
	v_cndmask_b32_e64 v25, v23, v25, s[10:11]
	v_fma_f32 v23, -v27, v23, v21
	v_cmp_lt_f32_e64 s[10:11], 0, v23
	v_mul_f32_e32 v81, v57, v57
	v_fmac_f32_e32 v81, v6, v6
	v_cndmask_b32_e64 v23, v25, v27, s[10:11]
	v_mul_f32_e32 v25, 0x37800000, v23
	v_cndmask_b32_e32 v23, v23, v25, vcc
	s_waitcnt lgkmcnt(0)
	v_add_f32_e32 v25, v29, v31
	ds_bpermute_b32 v27, v205, v25
	v_cmp_class_f32_e32 vcc, v21, v186
	v_fmac_f32_e32 v81, v42, v42
	v_fmac_f32_e32 v81, v34, v34
	v_cndmask_b32_e32 v21, v23, v21, vcc
	s_waitcnt lgkmcnt(0)
	v_add_f32_e32 v25, v25, v27
	ds_bpermute_b32 v27, v204, v25
	v_div_scale_f32 v23, s[0:1], v21, v21, s86
	v_rcp_f32_e32 v29, v23
	v_fma_f32 v82, v111, v17, -v71
	s_waitcnt lgkmcnt(0)
; __device__ __forceinline__ float shx(float v, int lane, int off) { return __builtin_bit_cast(float, __builtin_amdgcn_ds_bpermute((lane ^ off) << 2, __builtin_bit_cast(int, v))); }
; __device__ __forceinline__ void attn_unit(LAS unsigned char* lds, const bf16* Qh, const bf16* Kh, const bf16* VTh, const float* nrm, bf16* Y, const float* subln, float lam, int b, int h, int qb) {
;     ...
;         for (int r = 0; r < 16; ++r) { float a = 0.f;
; #pragma unroll
;             for (int blk = 0; blk < 4; ++blk) { const float d = o[blk][r] * rli[r] - cb[((wq * 4 + blk) * 16 + r) * 64 + lane]; o[blk][r] = d; a += d * d; }
;             ss[r] = a; }
; #pragma unroll
;         for (int r = 0; r < 16; ++r) {
; #pragma unroll
;             for (int off = 1; off < 32; off <<= 1) ss[r] += shx(ss[r], lane, off);
;             ss[r] = (1.0f - LAMBDA_INIT1) / sqrtf(ss[r] * (1.0f / 128.0f) + SUBLN_EPS); }
	v_add_f32_e32 v25, v25, v27
	ds_bpermute_b32 v27, v181, v25
	v_fma_f32 v78, v127, v17, -v83
	v_fma_f32 v71, v95, v17, -v87
	v_fma_f32 v64, v79, v17, -v103
	v_fma_f32 v17, -v23, v29, 1.0
	s_waitcnt lgkmcnt(0)
	v_add_f32_e32 v25, v25, v27
	v_fmamk_f32 v25, v25, 0x3c000000, v187
	v_mul_f32_e32 v27, 0x4f800000, v25
	v_cmp_gt_f32_e64 s[10:11], s85, v25
	v_fmac_f32_e32 v29, v17, v29
	v_div_scale_f32 v17, vcc, s86, v21, s86
	v_cndmask_b32_e64 v25, v25, v27, s[10:11]
	v_sqrt_f32_e32 v27, v25
	ds_bpermute_b32 v83, v207, v81
	v_mul_f32_e32 v31, v17, v29
	v_fma_f32 v79, -v23, v31, v17
	v_fmac_f32_e32 v31, v79, v29
	v_fma_f32 v17, -v23, v31, v17
	v_add_u32_e32 v23, -1, v27
	v_fma_f32 v79, -v23, v27, v25
	s_waitcnt lgkmcnt(0)
	v_add_f32_e32 v81, v81, v83
	v_cmp_ge_f32_e64 s[12:13], 0, v79
	v_add_u32_e32 v79, 1, v27
	ds_bpermute_b32 v83, v206, v81
	v_cndmask_b32_e64 v23, v27, v23, s[12:13]
	v_fma_f32 v27, -v79, v27, v25
	v_cmp_lt_f32_e64 s[12:13], 0, v27
	v_div_fmas_f32 v17, v17, v29, v31
	v_mul_f32_e32 v112, v58, v58
	v_cndmask_b32_e64 v23, v23, v79, s[12:13]
	v_mul_f32_e32 v27, 0x37800000, v23
	v_cndmask_b32_e64 v23, v23, v27, s[10:11]
	s_waitcnt lgkmcnt(0)
	v_add_f32_e32 v27, v81, v83
	ds_bpermute_b32 v79, v205, v27
	v_cmp_class_f32_e64 s[10:11], v25, v186
	v_fmac_f32_e32 v112, v8, v8
	v_fmac_f32_e32 v112, v43, v43
	v_cndmask_b32_e64 v23, v23, v25, s[10:11]
	s_waitcnt lgkmcnt(0)
	v_add_f32_e32 v27, v27, v79
	ds_bpermute_b32 v83, v204, v27
	v_div_fixup_f32 v79, v17, v21, s86
	v_div_scale_f32 v25, s[0:1], v23, v23, s86
	v_rcp_f32_e32 v81, v25
	s_waitcnt lgkmcnt(0)
	v_add_f32_e32 v21, v27, v83
	ds_bpermute_b32 v27, v181, v21
	v_fmac_f32_e32 v112, v35, v35
	v_fma_f32 v17, -v25, v81, 1.0
	v_fmac_f32_e32 v81, v17, v81
	v_div_scale_f32 v17, vcc, s86, v23, s86
	s_waitcnt lgkmcnt(0)
	v_add_f32_e32 v21, v21, v27
	v_fmamk_f32 v21, v21, 0x3c000000, v187
	v_mul_f32_e32 v27, 0x4f800000, v21
	v_cmp_gt_f32_e64 s[10:11], s85, v21
	ds_bpermute_b32 v83, v207, v112
	v_mul_f32_e32 v29, v17, v81
	v_cndmask_b32_e64 v21, v21, v27, s[10:11]
	v_sqrt_f32_e32 v27, v21
	v_fma_f32 v31, -v25, v29, v17
	v_fmac_f32_e32 v29, v31, v81
	v_fma_f32 v17, -v25, v29, v17
	v_add_u32_e32 v25, -1, v27
	v_fma_f32 v31, -v25, v27, v21
	s_waitcnt lgkmcnt(0)
	v_add_f32_e32 v83, v112, v83
	v_cmp_ge_f32_e64 s[12:13], 0, v31
	v_add_u32_e32 v31, 1, v27
	ds_bpermute_b32 v84, v206, v83
	v_cndmask_b32_e64 v25, v27, v25, s[12:13]
	v_fma_f32 v27, -v31, v27, v21
	v_cmp_lt_f32_e64 s[12:13], 0, v27
	v_div_fmas_f32 v17, v17, v81, v29
	v_div_fixup_f32 v81, v17, v23, s86
	v_cndmask_b32_e64 v25, v25, v31, s[12:13]
	v_mul_f32_e32 v27, 0x37800000, v25
	v_cndmask_b32_e64 v25, v25, v27, s[10:11]
	s_waitcnt lgkmcnt(0)
	v_add_f32_e32 v27, v83, v84
	ds_bpermute_b32 v31, v205, v27
	v_cmp_class_f32_e64 s[10:11], v21, v186
	v_mul_f32_e32 v113, v59, v59
	v_fmac_f32_e32 v113, v10, v10
	v_cndmask_b32_e64 v21, v25, v21, s[10:11]
	s_waitcnt lgkmcnt(0)
	v_add_f32_e32 v27, v27, v31
	ds_bpermute_b32 v31, v204, v27
	v_div_scale_f32 v25, s[0:1], v21, v21, s86
	v_rcp_f32_e32 v83, v25
	v_fmac_f32_e32 v113, v44, v44
	s_waitcnt lgkmcnt(0)
	v_add_f32_e32 v23, v27, v31
	ds_bpermute_b32 v27, v181, v23
	v_fmac_f32_e32 v113, v36, v36
	v_fma_f32 v17, -v25, v83, 1.0
	v_fmac_f32_e32 v83, v17, v83
	v_div_scale_f32 v17, vcc, s86, v21, s86
	s_waitcnt lgkmcnt(0)
	v_add_f32_e32 v23, v23, v27
	v_fmamk_f32 v23, v23, 0x3c000000, v187
	v_mul_f32_e32 v27, 0x4f800000, v23
	v_cmp_gt_f32_e64 s[10:11], s85, v23
	ds_bpermute_b32 v84, v207, v113
	v_mul_f32_e32 v29, v17, v83
	v_cndmask_b32_e64 v23, v23, v27, s[10:11]
	v_sqrt_f32_e32 v27, v23
	v_fma_f32 v31, -v25, v29, v17
	v_fmac_f32_e32 v29, v31, v83
	v_fma_f32 v17, -v25, v29, v17
	v_add_u32_e32 v25, -1, v27
	v_fma_f32 v31, -v25, v27, v23
	s_waitcnt lgkmcnt(0)
	v_add_f32_e32 v84, v113, v84
	v_cmp_ge_f32_e64 s[12:13], 0, v31
	v_add_u32_e32 v31, 1, v27
	ds_bpermute_b32 v85, v206, v84
	v_cndmask_b32_e64 v25, v27, v25, s[12:13]
	v_fma_f32 v27, -v31, v27, v23
	v_cmp_lt_f32_e64 s[12:13], 0, v27
	v_div_fmas_f32 v17, v17, v83, v29
	v_div_fixup_f32 v83, v17, v21, s86
	v_cndmask_b32_e64 v25, v25, v31, s[12:13]
	v_mul_f32_e32 v27, 0x37800000, v25
	v_cndmask_b32_e64 v25, v25, v27, s[10:11]
	s_waitcnt lgkmcnt(0)
	v_add_f32_e32 v27, v84, v85
	ds_bpermute_b32 v31, v205, v27
	v_cmp_class_f32_e64 s[10:11], v23, v186
	v_mul_f32_e32 v114, v60, v60
	v_fmac_f32_e32 v114, v12, v12
	v_cndmask_b32_e64 v23, v25, v23, s[10:11]
	s_waitcnt lgkmcnt(0)
	v_add_f32_e32 v27, v27, v31
	ds_bpermute_b32 v31, v204, v27
	v_div_scale_f32 v25, s[0:1], v23, v23, s86
	v_rcp_f32_e32 v84, v25
	v_fmac_f32_e32 v114, v45, v45
	s_waitcnt lgkmcnt(0)
	v_add_f32_e32 v21, v27, v31
	ds_bpermute_b32 v27, v181, v21
	v_fmac_f32_e32 v114, v37, v37
	v_fma_f32 v17, -v25, v84, 1.0
	v_fmac_f32_e32 v84, v17, v84
	v_div_scale_f32 v17, vcc, s86, v23, s86
	s_waitcnt lgkmcnt(0)
	v_add_f32_e32 v21, v21, v27
	v_fmamk_f32 v21, v21, 0x3c000000, v187
	v_mul_f32_e32 v27, 0x4f800000, v21
	v_cmp_gt_f32_e64 s[10:11], s85, v21
	ds_bpermute_b32 v85, v207, v114
	v_mul_f32_e32 v29, v17, v84
	v_cndmask_b32_e64 v21, v21, v27, s[10:11]
	v_sqrt_f32_e32 v27, v21
	v_fma_f32 v31, -v25, v29, v17
	v_fmac_f32_e32 v29, v31, v84
	v_fma_f32 v17, -v25, v29, v17
	v_add_u32_e32 v25, -1, v27
	v_fma_f32 v31, -v25, v27, v21
	s_waitcnt lgkmcnt(0)
	v_add_f32_e32 v85, v114, v85
	v_cmp_ge_f32_e64 s[12:13], 0, v31
	v_add_u32_e32 v31, 1, v27
	ds_bpermute_b32 v86, v206, v85
	v_cndmask_b32_e64 v25, v27, v25, s[12:13]
	v_fma_f32 v27, -v31, v27, v21
	v_cmp_lt_f32_e64 s[12:13], 0, v27
	v_div_fmas_f32 v17, v17, v84, v29
	v_div_fixup_f32 v84, v17, v23, s86
	v_cndmask_b32_e64 v25, v25, v31, s[12:13]
	v_mul_f32_e32 v27, 0x37800000, v25
	v_cndmask_b32_e64 v25, v25, v27, s[10:11]
	s_waitcnt lgkmcnt(0)
; __device__ __forceinline__ float shx(float v, int lane, int off) { return __builtin_bit_cast(float, __builtin_amdgcn_ds_bpermute((lane ^ off) << 2, __builtin_bit_cast(int, v))); }
; __device__ __forceinline__ void attn_unit(LAS unsigned char* lds, const bf16* Qh, const bf16* Kh, const bf16* VTh, const float* nrm, bf16* Y, const float* subln, float lam, int b, int h, int qb) {
;     ...
;         for (int r = 0; r < 16; ++r) { float a = 0.f;
; #pragma unroll
;             for (int blk = 0; blk < 4; ++blk) { const float d = o[blk][r] * rli[r] - cb[((wq * 4 + blk) * 16 + r) * 64 + lane]; o[blk][r] = d; a += d * d; }
;             ss[r] = a; }
; #pragma unroll
;         for (int r = 0; r < 16; ++r) {
; #pragma unroll
;             for (int off = 1; off < 32; off <<= 1) ss[r] += shx(ss[r], lane, off);
;             ss[r] = (1.0f - LAMBDA_INIT1) / sqrtf(ss[r] * (1.0f / 128.0f) + SUBLN_EPS); }
	v_add_f32_e32 v27, v85, v86
	ds_bpermute_b32 v31, v205, v27
	v_cmp_class_f32_e64 s[10:11], v21, v186
	v_mul_f32_e32 v19, v61, v61
	v_fmac_f32_e32 v19, v14, v14
	v_cndmask_b32_e64 v21, v25, v21, s[10:11]
	s_waitcnt lgkmcnt(0)
	v_add_f32_e32 v27, v27, v31
	ds_bpermute_b32 v31, v204, v27
	v_div_scale_f32 v25, s[0:1], v21, v21, s86
	v_rcp_f32_e32 v85, v25
	v_fmac_f32_e32 v19, v46, v46
	s_waitcnt lgkmcnt(0)
	v_add_f32_e32 v23, v27, v31
	ds_bpermute_b32 v27, v181, v23
	v_fmac_f32_e32 v19, v38, v38
	v_fma_f32 v17, -v25, v85, 1.0
	ds_bpermute_b32 v86, v207, v19
	v_fmac_f32_e32 v85, v17, v85
	s_waitcnt lgkmcnt(1)
	v_add_f32_e32 v23, v23, v27
	v_fmamk_f32 v23, v23, 0x3c000000, v187
	v_mul_f32_e32 v27, 0x4f800000, v23
	v_cmp_gt_f32_e64 s[10:11], s85, v23
	v_div_scale_f32 v17, vcc, s86, v21, s86
	s_nop 0
	v_cndmask_b32_e64 v23, v23, v27, s[10:11]
	v_sqrt_f32_e32 v27, v23
	v_mul_f32_e32 v29, v17, v85
	v_fma_f32 v31, -v25, v29, v17
	v_fmac_f32_e32 v29, v31, v85
	v_fma_f32 v17, -v25, v29, v17
	v_add_u32_e32 v25, -1, v27
	s_waitcnt lgkmcnt(0)
	v_add_f32_e32 v19, v19, v86
	v_fma_f32 v31, -v25, v27, v23
	ds_bpermute_b32 v86, v206, v19
	v_cmp_ge_f32_e64 s[12:13], 0, v31
	v_add_u32_e32 v31, 1, v27
	v_div_fmas_f32 v17, v17, v85, v29
	v_cndmask_b32_e64 v25, v27, v25, s[12:13]
	v_fma_f32 v27, -v31, v27, v23
	v_cmp_lt_f32_e64 s[12:13], 0, v27
	s_waitcnt lgkmcnt(0)
	v_add_f32_e32 v19, v19, v86
	v_div_fixup_f32 v85, v17, v21, s86
	v_cndmask_b32_e64 v25, v25, v31, s[12:13]
	v_mul_f32_e32 v27, 0x37800000, v25
	v_cndmask_b32_e64 v25, v25, v27, s[10:11]
	ds_bpermute_b32 v27, v205, v19
	v_cmp_class_f32_e64 s[10:11], v23, v186
	v_mul_f32_e32 v13, v62, v62
	v_fmac_f32_e32 v13, v16, v16
	v_cndmask_b32_e64 v23, v25, v23, s[10:11]
	s_waitcnt lgkmcnt(0)
	v_add_f32_e32 v19, v19, v27
	ds_bpermute_b32 v27, v204, v19
	v_div_scale_f32 v25, s[0:1], v23, v23, s86
	v_rcp_f32_e32 v31, v25
	v_fmac_f32_e32 v13, v47, v47
	s_waitcnt lgkmcnt(0)
	v_add_f32_e32 v19, v19, v27
	ds_bpermute_b32 v21, v181, v19
	v_fmac_f32_e32 v13, v39, v39
	v_fma_f32 v17, -v25, v31, 1.0
	ds_bpermute_b32 v86, v207, v13
	v_fmac_f32_e32 v31, v17, v31
	s_waitcnt lgkmcnt(1)
	v_add_f32_e32 v19, v19, v21
	v_fmamk_f32 v19, v19, 0x3c000000, v187
	v_mul_f32_e32 v21, 0x4f800000, v19
	v_cmp_gt_f32_e64 s[10:11], s85, v19
	v_div_scale_f32 v17, vcc, s86, v23, s86
	s_nop 0
	v_cndmask_b32_e64 v19, v19, v21, s[10:11]
	v_sqrt_f32_e32 v21, v19
	v_mul_f32_e32 v27, v17, v31
	v_fma_f32 v29, -v25, v27, v17
	v_fmac_f32_e32 v27, v29, v31
	v_fma_f32 v17, -v25, v27, v17
	v_add_u32_e32 v25, -1, v21
	s_waitcnt lgkmcnt(0)
	v_add_f32_e32 v13, v13, v86
	v_fma_f32 v29, -v25, v21, v19
	ds_bpermute_b32 v86, v206, v13
	v_cmp_ge_f32_e64 s[12:13], 0, v29
	v_add_u32_e32 v29, 1, v21
	v_div_fmas_f32 v17, v17, v31, v27
	v_cndmask_b32_e64 v25, v21, v25, s[12:13]
	v_fma_f32 v21, -v29, v21, v19
	v_cmp_lt_f32_e64 s[12:13], 0, v21
	s_waitcnt lgkmcnt(0)
	v_add_f32_e32 v13, v13, v86
	v_div_fixup_f32 v86, v17, v23, s86
	v_cndmask_b32_e64 v21, v25, v29, s[12:13]
	v_mul_f32_e32 v25, 0x37800000, v21
	v_cndmask_b32_e64 v21, v21, v25, s[10:11]
	ds_bpermute_b32 v25, v205, v13
	v_cmp_class_f32_e64 s[10:11], v19, v186
	v_mul_f32_e32 v15, v80, v80
	v_fmac_f32_e32 v15, v18, v18
	v_cndmask_b32_e64 v19, v21, v19, s[10:11]
	s_waitcnt lgkmcnt(0)
	v_add_f32_e32 v13, v13, v25
	ds_bpermute_b32 v25, v204, v13
	v_div_scale_f32 v21, s[0:1], v19, v19, s86
	v_rcp_f32_e32 v29, v21
	v_fmac_f32_e32 v15, v63, v63
	s_waitcnt lgkmcnt(0)
	v_add_f32_e32 v13, v13, v25
	ds_bpermute_b32 v23, v181, v13
	v_fmac_f32_e32 v15, v48, v48
	v_fma_f32 v17, -v21, v29, 1.0
	ds_bpermute_b32 v31, v207, v15
	v_fmac_f32_e32 v29, v17, v29
	s_waitcnt lgkmcnt(1)
	v_add_f32_e32 v13, v13, v23
	v_fmamk_f32 v13, v13, 0x3c000000, v187
	v_mul_f32_e32 v23, 0x4f800000, v13
	v_cmp_gt_f32_e64 s[10:11], s85, v13
	v_div_scale_f32 v17, vcc, s86, v19, s86
	s_nop 0
	v_cndmask_b32_e64 v13, v13, v23, s[10:11]
	v_sqrt_f32_e32 v23, v13
	v_mul_f32_e32 v25, v17, v29
	v_fma_f32 v27, -v21, v25, v17
	v_fmac_f32_e32 v25, v27, v29
	v_fma_f32 v17, -v21, v25, v17
	v_add_u32_e32 v21, -1, v23
	s_waitcnt lgkmcnt(0)
	v_add_f32_e32 v15, v15, v31
	v_fma_f32 v27, -v21, v23, v13
	ds_bpermute_b32 v31, v206, v15
	v_cmp_ge_f32_e64 s[12:13], 0, v27
	v_add_u32_e32 v27, 1, v23
	v_div_fmas_f32 v17, v17, v29, v25
	v_cndmask_b32_e64 v21, v23, v21, s[12:13]
	v_fma_f32 v23, -v27, v23, v13
	v_cmp_lt_f32_e64 s[12:13], 0, v23
	s_waitcnt lgkmcnt(0)
	v_add_f32_e32 v15, v15, v31
	v_div_fixup_f32 v87, v17, v19, s86
	v_cndmask_b32_e64 v21, v21, v27, s[12:13]
	v_mul_f32_e32 v23, 0x37800000, v21
	v_cndmask_b32_e64 v21, v21, v23, s[10:11]
	ds_bpermute_b32 v23, v205, v15
	v_cmp_class_f32_e64 s[10:11], v13, v186
	v_mul_f32_e32 v11, v72, v72
	v_fmac_f32_e32 v11, v20, v20
	v_cndmask_b32_e64 v13, v21, v13, s[10:11]
	s_waitcnt lgkmcnt(0)
	v_add_f32_e32 v15, v15, v23
	ds_bpermute_b32 v23, v204, v15
	v_div_scale_f32 v21, s[0:1], v13, v13, s86
	v_rcp_f32_e32 v27, v21
	v_fmac_f32_e32 v11, v65, v65
	s_waitcnt lgkmcnt(0)
	v_add_f32_e32 v15, v15, v23
	ds_bpermute_b32 v19, v181, v15
	v_fmac_f32_e32 v11, v49, v49
	v_fma_f32 v17, -v21, v27, 1.0
	ds_bpermute_b32 v29, v207, v11
	v_fmac_f32_e32 v27, v17, v27
	s_waitcnt lgkmcnt(1)
	v_add_f32_e32 v15, v15, v19
	v_fmamk_f32 v15, v15, 0x3c000000, v187
	v_mul_f32_e32 v19, 0x4f800000, v15
	v_cmp_gt_f32_e64 s[10:11], s85, v15
	v_div_scale_f32 v17, vcc, s86, v13, s86
	s_nop 0
	v_cndmask_b32_e64 v15, v15, v19, s[10:11]
	v_sqrt_f32_e32 v19, v15
	v_mul_f32_e32 v23, v17, v27
	v_fma_f32 v25, -v21, v23, v17
	v_fmac_f32_e32 v23, v25, v27
	v_fma_f32 v17, -v21, v23, v17
	v_add_u32_e32 v21, -1, v19
	s_waitcnt lgkmcnt(0)
; __device__ __forceinline__ float shx(float v, int lane, int off) { return __builtin_bit_cast(float, __builtin_amdgcn_ds_bpermute((lane ^ off) << 2, __builtin_bit_cast(int, v))); }
; __device__ __forceinline__ void attn_unit(LAS unsigned char* lds, const bf16* Qh, const bf16* Kh, const bf16* VTh, const float* nrm, bf16* Y, const float* subln, float lam, int b, int h, int qb) {
;     ...
;         for (int r = 0; r < 16; ++r) { float a = 0.f;
; #pragma unroll
;             for (int blk = 0; blk < 4; ++blk) { const float d = o[blk][r] * rli[r] - cb[((wq * 4 + blk) * 16 + r) * 64 + lane]; o[blk][r] = d; a += d * d; }
;             ss[r] = a; }
; #pragma unroll
;         for (int r = 0; r < 16; ++r) {
; #pragma unroll
;             for (int off = 1; off < 32; off <<= 1) ss[r] += shx(ss[r], lane, off);
;             ss[r] = (1.0f - LAMBDA_INIT1) / sqrtf(ss[r] * (1.0f / 128.0f) + SUBLN_EPS); }
	v_add_f32_e32 v11, v11, v29
	v_fma_f32 v25, -v21, v19, v15
	ds_bpermute_b32 v29, v206, v11
	v_cmp_ge_f32_e64 s[12:13], 0, v25
	v_add_u32_e32 v25, 1, v19
	v_div_fmas_f32 v17, v17, v27, v23
	v_cndmask_b32_e64 v21, v19, v21, s[12:13]
	v_fma_f32 v19, -v25, v19, v15
	v_cmp_lt_f32_e64 s[12:13], 0, v19
	s_waitcnt lgkmcnt(0)
	v_add_f32_e32 v11, v11, v29
	v_div_fixup_f32 v88, v17, v13, s86
	v_cndmask_b32_e64 v19, v21, v25, s[12:13]
	v_mul_f32_e32 v21, 0x37800000, v19
	v_cndmask_b32_e64 v19, v19, v21, s[10:11]
	ds_bpermute_b32 v21, v205, v11
	v_cmp_class_f32_e64 s[10:11], v15, v186
	v_mul_f32_e32 v9, v73, v73
	v_fmac_f32_e32 v9, v22, v22
	v_cndmask_b32_e64 v15, v19, v15, s[10:11]
	s_waitcnt lgkmcnt(0)
	v_add_f32_e32 v11, v11, v21
	ds_bpermute_b32 v21, v204, v11
	v_div_scale_f32 v19, s[0:1], v15, v15, s86
	v_rcp_f32_e32 v25, v19
	v_fmac_f32_e32 v9, v66, v66
	s_waitcnt lgkmcnt(0)
	v_add_f32_e32 v11, v11, v21
	ds_bpermute_b32 v17, v181, v11
	v_fmac_f32_e32 v9, v50, v50
	v_fma_f32 v13, -v19, v25, 1.0
	ds_bpermute_b32 v27, v207, v9
	v_fmac_f32_e32 v25, v13, v25
	s_waitcnt lgkmcnt(1)
	v_add_f32_e32 v11, v11, v17
	v_fmamk_f32 v11, v11, 0x3c000000, v187
	v_mul_f32_e32 v17, 0x4f800000, v11
	v_cmp_gt_f32_e64 s[10:11], s85, v11
	v_div_scale_f32 v13, vcc, s86, v15, s86
	s_nop 0
	v_cndmask_b32_e64 v11, v11, v17, s[10:11]
	v_sqrt_f32_e32 v17, v11
	v_mul_f32_e32 v21, v13, v25
	v_fma_f32 v23, -v19, v21, v13
	v_fmac_f32_e32 v21, v23, v25
	v_fma_f32 v13, -v19, v21, v13
	v_add_u32_e32 v19, -1, v17
	s_waitcnt lgkmcnt(0)
	v_add_f32_e32 v9, v9, v27
	v_fma_f32 v23, -v19, v17, v11
	ds_bpermute_b32 v27, v206, v9
	v_cmp_ge_f32_e64 s[12:13], 0, v23
	v_add_u32_e32 v23, 1, v17
	v_div_fmas_f32 v13, v13, v25, v21
	v_cndmask_b32_e64 v19, v17, v19, s[12:13]
	v_fma_f32 v17, -v23, v17, v11
	v_cmp_lt_f32_e64 s[12:13], 0, v17
	s_waitcnt lgkmcnt(0)
	v_add_f32_e32 v9, v9, v27
	v_div_fixup_f32 v89, v13, v15, s86
	v_cndmask_b32_e64 v17, v19, v23, s[12:13]
	v_mul_f32_e32 v19, 0x37800000, v17
	v_cndmask_b32_e64 v17, v17, v19, s[10:11]
	ds_bpermute_b32 v19, v205, v9
	v_cmp_class_f32_e64 s[10:11], v11, v186
	v_mul_f32_e32 v7, v74, v74
	v_fmac_f32_e32 v7, v24, v24
	v_cndmask_b32_e64 v11, v17, v11, s[10:11]
	s_waitcnt lgkmcnt(0)
	v_add_f32_e32 v9, v9, v19
	ds_bpermute_b32 v19, v204, v9
	v_div_scale_f32 v17, s[0:1], v11, v11, s86
	v_rcp_f32_e32 v23, v17
	v_fmac_f32_e32 v7, v67, v67
	s_waitcnt lgkmcnt(0)
	v_add_f32_e32 v9, v9, v19
	ds_bpermute_b32 v15, v181, v9
	v_fmac_f32_e32 v7, v51, v51
	v_fma_f32 v13, -v17, v23, 1.0
	ds_bpermute_b32 v25, v207, v7
	v_fmac_f32_e32 v23, v13, v23
	s_waitcnt lgkmcnt(1)
	v_add_f32_e32 v9, v9, v15
	v_fmamk_f32 v9, v9, 0x3c000000, v187
	v_mul_f32_e32 v15, 0x4f800000, v9
	v_cmp_gt_f32_e64 s[10:11], s85, v9
	v_div_scale_f32 v13, vcc, s86, v11, s86
	s_nop 0
	v_cndmask_b32_e64 v9, v9, v15, s[10:11]
	v_sqrt_f32_e32 v15, v9
	v_mul_f32_e32 v19, v13, v23
	v_fma_f32 v21, -v17, v19, v13
	v_fmac_f32_e32 v19, v21, v23
	v_fma_f32 v13, -v17, v19, v13
	v_add_u32_e32 v17, -1, v15
	s_waitcnt lgkmcnt(0)
	v_add_f32_e32 v7, v7, v25
	v_fma_f32 v21, -v17, v15, v9
	ds_bpermute_b32 v25, v206, v7
	v_cmp_ge_f32_e64 s[12:13], 0, v21
	v_add_u32_e32 v21, 1, v15
	v_div_fmas_f32 v13, v13, v23, v19
	v_cndmask_b32_e64 v17, v15, v17, s[12:13]
	v_fma_f32 v15, -v21, v15, v9
	v_cmp_lt_f32_e64 s[12:13], 0, v15
	s_waitcnt lgkmcnt(0)
	v_add_f32_e32 v7, v7, v25
	v_div_fixup_f32 v90, v13, v11, s86
	v_cndmask_b32_e64 v15, v17, v21, s[12:13]
	v_mul_f32_e32 v17, 0x37800000, v15
	v_cndmask_b32_e64 v15, v15, v17, s[10:11]
	ds_bpermute_b32 v17, v205, v7
	v_cmp_class_f32_e64 s[10:11], v9, v186
	v_mul_f32_e32 v5, v75, v75
	v_fmac_f32_e32 v5, v26, v26
	v_cndmask_b32_e64 v9, v15, v9, s[10:11]
	s_waitcnt lgkmcnt(0)
	v_add_f32_e32 v7, v7, v17
	ds_bpermute_b32 v17, v204, v7
	v_div_scale_f32 v15, s[0:1], v9, v9, s86
	v_rcp_f32_e32 v21, v15
	v_fmac_f32_e32 v5, v68, v68
	s_waitcnt lgkmcnt(0)
	v_add_f32_e32 v7, v7, v17
	ds_bpermute_b32 v13, v181, v7
	v_fmac_f32_e32 v5, v52, v52
	v_fma_f32 v11, -v15, v21, 1.0
	ds_bpermute_b32 v23, v207, v5
	v_fmac_f32_e32 v21, v11, v21
	s_waitcnt lgkmcnt(1)
	v_add_f32_e32 v7, v7, v13
	v_fmamk_f32 v7, v7, 0x3c000000, v187
	v_mul_f32_e32 v13, 0x4f800000, v7
	v_cmp_gt_f32_e64 s[10:11], s85, v7
	v_div_scale_f32 v11, vcc, s86, v9, s86
	s_nop 0
	v_cndmask_b32_e64 v7, v7, v13, s[10:11]
	v_sqrt_f32_e32 v13, v7
	v_mul_f32_e32 v17, v11, v21
	v_fma_f32 v19, -v15, v17, v11
	v_fmac_f32_e32 v17, v19, v21
	v_fma_f32 v11, -v15, v17, v11
	v_add_u32_e32 v15, -1, v13
	s_waitcnt lgkmcnt(0)
	v_add_f32_e32 v5, v5, v23
	v_fma_f32 v19, -v15, v13, v7
	ds_bpermute_b32 v23, v206, v5
	v_cmp_ge_f32_e64 s[12:13], 0, v19
	v_add_u32_e32 v19, 1, v13
	v_div_fmas_f32 v11, v11, v21, v17
	v_cndmask_b32_e64 v15, v13, v15, s[12:13]
	v_fma_f32 v13, -v19, v13, v7
	v_cmp_lt_f32_e64 s[12:13], 0, v13
	s_waitcnt lgkmcnt(0)
	v_add_f32_e32 v5, v5, v23
	v_div_fixup_f32 v91, v11, v9, s86
	v_cndmask_b32_e64 v13, v15, v19, s[12:13]
	v_mul_f32_e32 v15, 0x37800000, v13
	v_cndmask_b32_e64 v13, v13, v15, s[10:11]
	ds_bpermute_b32 v15, v205, v5
	v_cmp_class_f32_e64 s[10:11], v7, v186
	v_mul_f32_e32 v3, v76, v76
	v_fmac_f32_e32 v3, v28, v28
	v_cndmask_b32_e64 v7, v13, v7, s[10:11]
	s_waitcnt lgkmcnt(0)
	v_add_f32_e32 v5, v5, v15
	ds_bpermute_b32 v15, v204, v5
	v_div_scale_f32 v13, s[0:1], v7, v7, s86
	v_rcp_f32_e32 v19, v13
	v_fmac_f32_e32 v3, v69, v69
	s_waitcnt lgkmcnt(0)
	v_add_f32_e32 v5, v5, v15
	ds_bpermute_b32 v11, v181, v5
	v_fmac_f32_e32 v3, v53, v53
	v_fma_f32 v9, -v13, v19, 1.0
	ds_bpermute_b32 v21, v207, v3
	v_fmac_f32_e32 v19, v9, v19
	s_waitcnt lgkmcnt(1)
; __device__ __forceinline__ float shx(float v, int lane, int off) { return __builtin_bit_cast(float, __builtin_amdgcn_ds_bpermute((lane ^ off) << 2, __builtin_bit_cast(int, v))); }
; __device__ __forceinline__ void attn_unit(LAS unsigned char* lds, const bf16* Qh, const bf16* Kh, const bf16* VTh, const float* nrm, bf16* Y, const float* subln, float lam, int b, int h, int qb) {
;     ...
; #pragma unroll
;         for (int r = 0; r < 16; ++r) {
; #pragma unroll
;             for (int off = 1; off < 32; off <<= 1) ss[r] += shx(ss[r], lane, off);
;             ss[r] = (1.0f - LAMBDA_INIT1) / sqrtf(ss[r] * (1.0f / 128.0f) + SUBLN_EPS); }
;         bf16* yb = Y + (tokb + qw0) * (size_t)D + h * 128 + r32;
; #pragma unroll
;         for (int blk = 0; blk < 4; ++blk) { const float g = subln[blk * 32 + r32];
	v_add_f32_e32 v5, v5, v11
	v_fmamk_f32 v5, v5, 0x3c000000, v187
	v_mul_f32_e32 v11, 0x4f800000, v5
	v_cmp_gt_f32_e64 s[10:11], s85, v5
	v_div_scale_f32 v9, vcc, s86, v7, s86
	s_nop 0
	v_cndmask_b32_e64 v5, v5, v11, s[10:11]
	v_sqrt_f32_e32 v11, v5
	v_mul_f32_e32 v15, v9, v19
	v_fma_f32 v17, -v13, v15, v9
	v_fmac_f32_e32 v15, v17, v19
	v_fma_f32 v9, -v13, v15, v9
	v_add_u32_e32 v13, -1, v11
	s_waitcnt lgkmcnt(0)
	v_add_f32_e32 v3, v3, v21
	v_fma_f32 v17, -v13, v11, v5
	ds_bpermute_b32 v21, v206, v3
	v_cmp_ge_f32_e64 s[12:13], 0, v17
	v_add_u32_e32 v17, 1, v11
	v_div_fmas_f32 v9, v9, v19, v15
	v_cndmask_b32_e64 v13, v11, v13, s[12:13]
	v_fma_f32 v11, -v17, v11, v5
	v_cmp_lt_f32_e64 s[12:13], 0, v11
	s_waitcnt lgkmcnt(0)
	v_add_f32_e32 v3, v3, v21
	v_div_fixup_f32 v92, v9, v7, s86
	v_cndmask_b32_e64 v11, v13, v17, s[12:13]
	v_mul_f32_e32 v13, 0x37800000, v11
	v_cndmask_b32_e64 v11, v11, v13, s[10:11]
	ds_bpermute_b32 v13, v205, v3
	v_mul_f32_e32 v1, v77, v77
	v_cmp_class_f32_e64 s[10:11], v5, v186
	v_fmac_f32_e32 v1, v30, v30
	v_fmac_f32_e32 v1, v70, v70
	s_waitcnt lgkmcnt(0)
	v_add_f32_e32 v3, v3, v13
	ds_bpermute_b32 v13, v204, v3
	v_cndmask_b32_e64 v5, v11, v5, s[10:11]
	v_div_scale_f32 v11, s[0:1], v5, v5, s86
	v_fmac_f32_e32 v1, v54, v54
	s_waitcnt lgkmcnt(0)
	v_add_f32_e32 v3, v3, v13
	ds_bpermute_b32 v9, v181, v3
	v_rcp_f32_e32 v17, v11
	ds_bpermute_b32 v19, v207, v1
	v_mul_f32_e32 v0, v78, v78
	v_fmac_f32_e32 v0, v82, v82
	s_waitcnt lgkmcnt(1)
	v_add_f32_e32 v3, v3, v9
	v_fmamk_f32 v3, v3, 0x3c000000, v187
	v_mul_f32_e32 v9, 0x4f800000, v3
	v_cmp_gt_f32_e64 s[10:11], s85, v3
	v_fma_f32 v7, -v11, v17, 1.0
	v_fmac_f32_e32 v17, v7, v17
	v_cndmask_b32_e64 v3, v3, v9, s[10:11]
	v_div_scale_f32 v7, vcc, s86, v5, s86
	v_sqrt_f32_e32 v9, v3
	v_mul_f32_e32 v13, v7, v17
	s_waitcnt lgkmcnt(0)
	v_add_f32_e32 v1, v1, v19
	v_fma_f32 v15, -v11, v13, v7
	ds_bpermute_b32 v19, v206, v1
	v_fmac_f32_e32 v13, v15, v17
	v_fma_f32 v7, -v11, v13, v7
	v_add_u32_e32 v11, -1, v9
	v_fma_f32 v15, -v11, v9, v3
	v_cmp_ge_f32_e64 s[12:13], 0, v15
	v_add_u32_e32 v15, 1, v9
	s_waitcnt lgkmcnt(0)
	v_add_f32_e32 v1, v1, v19
	v_cndmask_b32_e64 v11, v9, v11, s[12:13]
	v_fma_f32 v9, -v15, v9, v3
	v_lshlrev_b32_e32 v19, 2, v202
	v_cmp_lt_f32_e64 s[12:13], 0, v9
	global_load_dword v97, v19, s[22:23]
	v_div_fmas_f32 v7, v7, v17, v13
	v_cndmask_b32_e64 v9, v11, v15, s[12:13]
	v_mul_f32_e32 v11, 0x37800000, v9
	v_cndmask_b32_e64 v9, v9, v11, s[10:11]
	ds_bpermute_b32 v11, v205, v1
	v_div_fixup_f32 v93, v7, v5, s86
	v_cmp_class_f32_e64 s[10:11], v3, v186
	v_fmac_f32_e32 v0, v71, v71
	v_fmac_f32_e32 v0, v64, v64
	s_waitcnt lgkmcnt(0)
	v_add_f32_e32 v1, v1, v11
	ds_bpermute_b32 v11, v204, v1
	v_cndmask_b32_e64 v3, v9, v3, s[10:11]
	v_div_scale_f32 v9, s[0:1], v3, v3, s86
	v_rcp_f32_e32 v15, v9
	s_waitcnt lgkmcnt(0)
	v_add_f32_e32 v1, v1, v11
	ds_bpermute_b32 v7, v181, v1
	ds_bpermute_b32 v17, v207, v0
	v_fma_f32 v5, -v9, v15, 1.0
	v_fmac_f32_e32 v15, v5, v15
	v_div_scale_f32 v5, vcc, s86, v3, s86
	s_waitcnt lgkmcnt(1)
	v_add_f32_e32 v1, v1, v7
	v_fmamk_f32 v1, v1, 0x3c000000, v187
	v_mul_f32_e32 v7, 0x4f800000, v1
	v_cmp_gt_f32_e64 s[10:11], s85, v1
	v_mul_f32_e32 v11, v5, v15
	v_fma_f32 v13, -v9, v11, v5
	v_cndmask_b32_e64 v1, v1, v7, s[10:11]
	v_sqrt_f32_e32 v7, v1
	v_fmac_f32_e32 v11, v13, v15
	v_fma_f32 v5, -v9, v11, v5
	s_waitcnt lgkmcnt(0)
	v_add_f32_e32 v0, v0, v17
	v_add_u32_e32 v9, -1, v7
	v_fma_f32 v13, -v9, v7, v1
	ds_bpermute_b32 v17, v206, v0
	v_cmp_ge_f32_e64 s[12:13], 0, v13
	v_add_u32_e32 v13, 1, v7
	v_div_fmas_f32 v5, v5, v15, v11
	v_cndmask_b32_e64 v9, v7, v9, s[12:13]
	v_fma_f32 v7, -v13, v7, v1
	v_cmp_lt_f32_e64 s[12:13], 0, v7
	s_waitcnt lgkmcnt(0)
	v_add_f32_e32 v0, v0, v17
	v_div_fixup_f32 v94, v5, v3, s86
	v_cndmask_b32_e64 v7, v9, v13, s[12:13]
	v_mul_f32_e32 v9, 0x37800000, v7
	v_cndmask_b32_e64 v7, v7, v9, s[10:11]
	ds_bpermute_b32 v9, v205, v0
	global_load_dword v102, v19, s[22:23] offset:128
	global_load_dword v103, v19, s[22:23] offset:256
	global_load_dword v104, v19, s[22:23] offset:384
	v_cmp_class_f32_e64 s[10:11], v1, v186
	v_mul_f32_e32 v2, v2, v79
	v_lshlrev_b32_e32 v176, 1, v202
	s_waitcnt lgkmcnt(0)
	v_add_f32_e32 v0, v0, v9
	ds_bpermute_b32 v9, v204, v0
	v_cndmask_b32_e64 v1, v7, v1, s[10:11]
	v_div_scale_f32 v7, s[0:1], v1, v1, s86
	v_rcp_f32_e32 v13, v7
	s_waitcnt lgkmcnt(0)
	v_add_f32_e32 v0, v0, v9
	ds_bpermute_b32 v5, v181, v0
	v_mul_f32_e32 v4, v4, v81
	v_fma_f32 v3, -v7, v13, 1.0
	v_fmac_f32_e32 v13, v3, v13
	v_div_scale_f32 v3, vcc, s86, v1, s86
	s_waitcnt lgkmcnt(0)
	v_add_f32_e32 v0, v0, v5
	v_fmamk_f32 v0, v0, 0x3c000000, v187
	v_mul_f32_e32 v5, 0x4f800000, v0
	v_cmp_gt_f32_e64 s[10:11], s85, v0
	v_mul_f32_e32 v9, v3, v13
	v_fma_f32 v11, -v7, v9, v3
	v_cndmask_b32_e64 v0, v0, v5, s[10:11]
	v_sqrt_f32_e32 v5, v0
	v_fmac_f32_e32 v9, v11, v13
	v_fma_f32 v3, -v7, v9, v3
	v_div_fmas_f32 v3, v3, v13, v9
	v_add_u32_e32 v7, -1, v5
	v_fma_f32 v11, -v7, v5, v0
	v_cmp_ge_f32_e64 s[12:13], 0, v11
	v_add_u32_e32 v11, 1, v5
	v_div_fixup_f32 v95, v3, v1, s86
	v_cndmask_b32_e64 v7, v5, v7, s[12:13]
	v_fma_f32 v5, -v11, v5, v0
	v_cmp_lt_f32_e64 s[12:13], 0, v5
	s_waitcnt vmcnt(3)
; __device__ __forceinline__ unsigned f2bf(float f) { unsigned u = __builtin_bit_cast(unsigned, f); return (u + 0x7fffu + ((u >> 16) & 1u)) >> 16; }
; __device__ __forceinline__ int crow(int r, int hi) { return (r & 3) + 8 * (r >> 2) + 4 * hi; }
; __device__ __forceinline__ void attn_unit(LAS unsigned char* lds, const bf16* Qh, const bf16* Kh, const bf16* VTh, const float* nrm, bf16* Y, const float* subln, float lam, int b, int h, int qb) {
;     ...
;         bf16* yb = Y + (tokb + qw0) * (size_t)D + h * 128 + r32;
; #pragma unroll
;         for (int blk = 0; blk < 4; ++blk) { const float g = subln[blk * 32 + r32];
; #pragma unroll
;             for (int r = 0; r < 16; ++r) yb[(size_t)crow(r, hi) * D + blk * 32] = (bf16)f2bf(o[blk][r] * ss[r] * g); }
	v_mul_f32_e32 v2, v2, v97
	v_mul_f32_e32 v4, v4, v97
	v_cndmask_b32_e64 v5, v7, v11, s[12:13]
	v_mul_f32_e32 v7, 0x37800000, v5
	v_cndmask_b32_e64 v5, v5, v7, s[10:11]
	v_cmp_class_f32_e64 s[10:11], v0, v186
	v_mul_f32_e32 v6, v6, v83
	v_mul_f32_e32 v6, v6, v97
	v_cndmask_b32_e64 v0, v5, v0, s[10:11]
	v_div_scale_f32 v5, s[0:1], v0, v0, s86
	v_rcp_f32_e32 v7, v5
	s_lshl_b32 s0, s80, 24
	s_add_u32 s3, s28, s0
	s_addc_u32 s6, s29, 0
	v_fma_f32 v1, -v5, v7, 1.0
	s_lshl_b64 s[0:1], s[18:19], 12
	v_fmac_f32_e32 v7, v1, v7
	v_div_scale_f32 v1, vcc, s86, v0, s86
	s_add_u32 s3, s3, s0
	v_mul_f32_e32 v3, v1, v7
	s_addc_u32 s6, s6, s1
	s_lshl_b32 s0, s5, 7
	v_fma_f32 v9, -v5, v3, v1
	s_ashr_i32 s1, s0, 31
	v_fmac_f32_e32 v3, v9, v7
	s_lshl_b64 s[0:1], s[0:1], 1
	v_fma_f32 v1, -v5, v3, v1
	s_add_u32 s0, s3, s0
	v_div_fmas_f32 v1, v1, v7, v3
	s_addc_u32 s1, s6, s1
	s_mov_b64 s[98:99], s[0:1]
	v_div_fixup_f32 v96, v1, v0, s86
	v_lshl_add_u64 v[0:1], s[0:1], 0, v[176:177]
	v_lshlrev_b32_e32 v176, 14, v201
	v_mov_b32_e32 v112, s81
	v_lshlrev_b32_e32 v112, 8, v112
	v_and_b32_e32 v112, 0xc000, v112
	v_lshl_add_u32 v112, v201, 10, v112
	v_lshl_add_u32 v112, v201, 6, v112
	v_lshl_add_u32 v112, v202, 1, v112
	v_bfe_u32 v3, v2, 16, 1
	v_add3_u32 v5, v2, v3, s87
	v_lshl_add_u64 v[2:3], v[0:1], 0, v[176:177]
	ds_write_b16_d16_hi v112, v5 offset:0
	v_bfe_u32 v5, v4, 16, 1
	v_add3_u32 v7, v4, v5, s87
	v_or_b32_e32 v4, 0x1000, v176
	v_mov_b32_e32 v5, v177
	v_lshl_add_u64 v[98:99], v[0:1], 0, v[4:5]
	ds_write_b16_d16_hi v112, v7 offset:272
	v_bfe_u32 v7, v6, 16, 1
	v_add3_u32 v9, v6, v7, s87
	v_or_b32_e32 v6, 0x2000, v176
	v_mov_b32_e32 v7, v177
	v_mul_f32_e32 v8, v8, v84
	v_lshl_add_u64 v[98:99], v[0:1], 0, v[6:7]
	v_mul_f32_e32 v8, v8, v97
	ds_write_b16_d16_hi v112, v9 offset:544
	v_bfe_u32 v9, v8, 16, 1
	v_add3_u32 v11, v8, v9, s87
	v_or_b32_e32 v8, 0x3000, v176
	v_mov_b32_e32 v9, v177
	v_mul_f32_e32 v10, v10, v85
	v_lshl_add_u64 v[98:99], v[0:1], 0, v[8:9]
	v_mul_f32_e32 v10, v10, v97
	ds_write_b16_d16_hi v112, v11 offset:816
	v_bfe_u32 v11, v10, 16, 1
	v_add3_u32 v13, v10, v11, s87
	v_or_b32_e32 v10, 0x8000, v176
	v_mov_b32_e32 v11, v177
	v_mul_f32_e32 v12, v12, v86
	v_lshl_add_u64 v[98:99], v[0:1], 0, v[10:11]
	v_mul_f32_e32 v12, v12, v97
	ds_write_b16_d16_hi v112, v13 offset:2176
	v_bfe_u32 v13, v12, 16, 1
	v_add3_u32 v15, v12, v13, s87
	v_or_b32_e32 v12, 0x9000, v176
	v_mov_b32_e32 v13, v177
	v_mul_f32_e32 v14, v14, v87
	v_lshl_add_u64 v[98:99], v[0:1], 0, v[12:13]
	v_mul_f32_e32 v14, v14, v97
	ds_write_b16_d16_hi v112, v15 offset:2448
	v_bfe_u32 v15, v14, 16, 1
	v_add3_u32 v17, v14, v15, s87
	v_or_b32_e32 v14, 0xa000, v176
	v_mov_b32_e32 v15, v177
	v_mul_f32_e32 v16, v16, v88
	v_lshl_add_u64 v[98:99], v[0:1], 0, v[14:15]
	v_mul_f32_e32 v16, v16, v97
	ds_write_b16_d16_hi v112, v17 offset:2720
	v_bfe_u32 v17, v16, 16, 1
	v_add3_u32 v19, v16, v17, s87
	v_or_b32_e32 v16, 0xb000, v176
	v_mov_b32_e32 v17, v177
	v_mul_f32_e32 v18, v18, v89
	v_lshl_add_u64 v[98:99], v[0:1], 0, v[16:17]
	v_mul_f32_e32 v18, v18, v97
	ds_write_b16_d16_hi v112, v19 offset:2992
	v_bfe_u32 v19, v18, 16, 1
	v_add3_u32 v21, v18, v19, s87
	v_or_b32_e32 v18, 0x10000, v176
	v_mov_b32_e32 v19, v177
	v_mul_f32_e32 v20, v20, v90
	v_lshl_add_u64 v[98:99], v[0:1], 0, v[18:19]
	v_mul_f32_e32 v20, v20, v97
	ds_write_b16_d16_hi v112, v21 offset:4352
	v_bfe_u32 v21, v20, 16, 1
	v_add3_u32 v23, v20, v21, s87
	v_or_b32_e32 v20, 0x11000, v176
	v_mov_b32_e32 v21, v177
	v_mul_f32_e32 v22, v22, v91
	v_lshl_add_u64 v[98:99], v[0:1], 0, v[20:21]
	v_mul_f32_e32 v22, v22, v97
	ds_write_b16_d16_hi v112, v23 offset:4624
	v_bfe_u32 v23, v22, 16, 1
	v_add3_u32 v25, v22, v23, s87
	v_or_b32_e32 v22, 0x12000, v176
	v_mov_b32_e32 v23, v177
	v_mul_f32_e32 v24, v24, v92
	v_lshl_add_u64 v[98:99], v[0:1], 0, v[22:23]
	v_mul_f32_e32 v24, v24, v97
	ds_write_b16_d16_hi v112, v25 offset:4896
	v_bfe_u32 v25, v24, 16, 1
	v_add3_u32 v27, v24, v25, s87
	v_or_b32_e32 v24, 0x13000, v176
	v_mov_b32_e32 v25, v177
	v_mul_f32_e32 v26, v26, v93
	v_lshl_add_u64 v[98:99], v[0:1], 0, v[24:25]
	v_mul_f32_e32 v26, v26, v97
	ds_write_b16_d16_hi v112, v27 offset:5168
	v_bfe_u32 v27, v26, 16, 1
	v_add3_u32 v29, v26, v27, s87
	v_or_b32_e32 v26, 0x18000, v176
	v_mov_b32_e32 v27, v177
	v_mul_f32_e32 v28, v28, v94
	v_lshl_add_u64 v[98:99], v[0:1], 0, v[26:27]
	v_mul_f32_e32 v28, v28, v97
	ds_write_b16_d16_hi v112, v29 offset:6528
	v_bfe_u32 v29, v28, 16, 1
	v_add3_u32 v31, v28, v29, s87
	v_or_b32_e32 v28, 0x19000, v176
	v_mov_b32_e32 v29, v177
	v_mul_f32_e32 v30, v30, v95
	v_lshl_add_u64 v[98:99], v[0:1], 0, v[28:29]
	v_mul_f32_e32 v30, v97, v30
	ds_write_b16_d16_hi v112, v31 offset:6800
	v_bfe_u32 v31, v30, 16, 1
	v_mul_f32_e32 v82, v82, v96
	v_add3_u32 v100, v30, v31, s87
	v_or_b32_e32 v30, 0x1a000, v176
	v_mov_b32_e32 v31, v177
	v_mul_f32_e32 v82, v97, v82
	v_lshl_add_u64 v[98:99], v[0:1], 0, v[30:31]
	v_bfe_u32 v97, v82, 16, 1
	v_or_b32_e32 v176, 0x1b000, v176
	v_mul_f32_e32 v55, v55, v79
	ds_write_b16_d16_hi v112, v100 offset:7072
	v_add3_u32 v82, v82, v97, s87
	v_lshl_add_u64 v[98:99], v[0:1], 0, v[176:177]
	s_waitcnt vmcnt(2)
; __device__ __forceinline__ unsigned f2bf(float f) { unsigned u = __builtin_bit_cast(unsigned, f); return (u + 0x7fffu + ((u >> 16) & 1u)) >> 16; }
; __device__ __forceinline__ int crow(int r, int hi) { return (r & 3) + 8 * (r >> 2) + 4 * hi; }
; __device__ __forceinline__ void attn_unit(LAS unsigned char* lds, const bf16* Qh, const bf16* Kh, const bf16* VTh, const float* nrm, bf16* Y, const float* subln, float lam, int b, int h, int qb) {
;     ...
;         bf16* yb = Y + (tokb + qw0) * (size_t)D + h * 128 + r32;
; #pragma unroll
;         for (int blk = 0; blk < 4; ++blk) { const float g = subln[blk * 32 + r32];
; #pragma unroll
;             for (int r = 0; r < 16; ++r) yb[(size_t)crow(r, hi) * D + blk * 32] = (bf16)f2bf(o[blk][r] * ss[r] * g); }
	v_mul_f32_e32 v55, v55, v102
	ds_write_b16_d16_hi v112, v82 offset:7344
	v_bfe_u32 v82, v55, 16, 1
	v_add3_u32 v55, v55, v82, s87
	ds_write_b16_d16_hi v112, v55 offset:64
	v_mul_f32_e32 v55, v56, v81
	v_mul_f32_e32 v55, v55, v102
	v_lshl_add_u64 v[98:99], v[0:1], 0, 64
	v_bfe_u32 v56, v55, 16, 1
	v_add3_u32 v55, v55, v56, s87
	v_lshl_add_u64 v[100:101], v[98:99], 0, v[4:5]
	ds_write_b16_d16_hi v112, v55 offset:336
	v_mul_f32_e32 v55, v57, v83
	v_mul_f32_e32 v55, v55, v102
	v_bfe_u32 v56, v55, 16, 1
	v_add3_u32 v55, v55, v56, s87
	v_lshl_add_u64 v[56:57], v[98:99], 0, v[6:7]
	ds_write_b16_d16_hi v112, v55 offset:608
	v_mul_f32_e32 v55, v58, v84
	v_mul_f32_e32 v55, v55, v102
	v_bfe_u32 v56, v55, 16, 1
	v_add3_u32 v55, v55, v56, s87
	v_lshl_add_u64 v[56:57], v[98:99], 0, v[8:9]
	ds_write_b16_d16_hi v112, v55 offset:880
	v_mul_f32_e32 v55, v59, v85
	v_mul_f32_e32 v55, v55, v102
	v_bfe_u32 v56, v55, 16, 1
	v_add3_u32 v55, v55, v56, s87
	v_lshl_add_u64 v[56:57], v[98:99], 0, v[10:11]
	ds_write_b16_d16_hi v112, v55 offset:2240
	v_mul_f32_e32 v55, v60, v86
	v_mul_f32_e32 v55, v55, v102
	v_bfe_u32 v56, v55, 16, 1
	v_add3_u32 v55, v55, v56, s87
	v_lshl_add_u64 v[56:57], v[98:99], 0, v[12:13]
	ds_write_b16_d16_hi v112, v55 offset:2512
	v_mul_f32_e32 v55, v61, v87
	v_mul_f32_e32 v55, v55, v102
	v_bfe_u32 v56, v55, 16, 1
	v_add3_u32 v55, v55, v56, s87
	v_lshl_add_u64 v[56:57], v[98:99], 0, v[14:15]
	ds_write_b16_d16_hi v112, v55 offset:2784
	v_mul_f32_e32 v55, v62, v88
	v_mul_f32_e32 v55, v55, v102
	v_bfe_u32 v56, v55, 16, 1
	v_add3_u32 v55, v55, v56, s87
	v_lshl_add_u64 v[56:57], v[98:99], 0, v[16:17]
	ds_write_b16_d16_hi v112, v55 offset:3056
	v_mul_f32_e32 v55, v80, v89
	v_mul_f32_e32 v55, v55, v102
	v_bfe_u32 v56, v55, 16, 1
	v_add3_u32 v55, v55, v56, s87
	v_lshl_add_u64 v[56:57], v[98:99], 0, v[18:19]
	ds_write_b16_d16_hi v112, v55 offset:4416
	v_mul_f32_e32 v55, v72, v90
	v_mul_f32_e32 v55, v55, v102
	v_bfe_u32 v56, v55, 16, 1
	v_add3_u32 v55, v55, v56, s87
	v_lshl_add_u64 v[56:57], v[98:99], 0, v[20:21]
	ds_write_b16_d16_hi v112, v55 offset:4688
	v_mul_f32_e32 v55, v73, v91
	v_mul_f32_e32 v55, v55, v102
	v_bfe_u32 v56, v55, 16, 1
	v_add3_u32 v55, v55, v56, s87
	v_lshl_add_u64 v[56:57], v[98:99], 0, v[22:23]
	ds_write_b16_d16_hi v112, v55 offset:4960
	v_mul_f32_e32 v55, v74, v92
	v_mul_f32_e32 v55, v55, v102
	v_bfe_u32 v56, v55, 16, 1
	v_add3_u32 v55, v55, v56, s87
	v_lshl_add_u64 v[56:57], v[98:99], 0, v[24:25]
	ds_write_b16_d16_hi v112, v55 offset:5232
	v_mul_f32_e32 v55, v75, v93
	v_mul_f32_e32 v55, v55, v102
	v_bfe_u32 v56, v55, 16, 1
	v_add3_u32 v55, v55, v56, s87
	v_lshl_add_u64 v[56:57], v[98:99], 0, v[26:27]
	ds_write_b16_d16_hi v112, v55 offset:6592
	v_mul_f32_e32 v55, v76, v94
	v_mul_f32_e32 v55, v55, v102
	v_bfe_u32 v56, v55, 16, 1
	v_add3_u32 v55, v55, v56, s87
	v_lshl_add_u64 v[56:57], v[98:99], 0, v[28:29]
	ds_write_b16_d16_hi v112, v55 offset:6864
	v_mul_f32_e32 v55, v77, v95
	v_mul_f32_e32 v55, v55, v102
	v_bfe_u32 v56, v55, 16, 1
	v_add3_u32 v55, v55, v56, s87
	v_lshl_add_u64 v[56:57], v[98:99], 0, v[30:31]
	ds_write_b16_d16_hi v112, v55 offset:7136
	v_mul_f32_e32 v55, v78, v96
	v_mul_f32_e32 v55, v55, v102
	v_bfe_u32 v56, v55, 16, 1
	v_mul_f32_e32 v40, v40, v79
	v_add3_u32 v55, v55, v56, s87
	v_lshl_add_u64 v[56:57], v[98:99], 0, v[176:177]
	s_waitcnt vmcnt(1)
	v_mul_f32_e32 v40, v40, v103
	ds_write_b16_d16_hi v112, v55 offset:7408
	v_bfe_u32 v55, v40, 16, 1
	v_add3_u32 v40, v40, v55, s87
	ds_write_b16_d16_hi v112, v40 offset:128
	v_mul_f32_e32 v40, v41, v81
	s_mov_b64 s[0:1], 0x80
	v_mul_f32_e32 v40, v40, v103
	v_lshl_add_u64 v[56:57], v[0:1], 0, s[0:1]
	v_bfe_u32 v41, v40, 16, 1
	v_add3_u32 v55, v40, v41, s87
	v_lshl_add_u64 v[40:41], v[56:57], 0, v[4:5]
	ds_write_b16_d16_hi v112, v55 offset:400
	v_mul_f32_e32 v40, v42, v83
	v_mul_f32_e32 v40, v40, v103
	v_bfe_u32 v41, v40, 16, 1
	v_add3_u32 v42, v40, v41, s87
	v_lshl_add_u64 v[40:41], v[56:57], 0, v[6:7]
	ds_write_b16_d16_hi v112, v42 offset:672
	v_mul_f32_e32 v40, v43, v84
	v_mul_f32_e32 v40, v40, v103
	v_bfe_u32 v41, v40, 16, 1
	v_add3_u32 v42, v40, v41, s87
	v_lshl_add_u64 v[40:41], v[56:57], 0, v[8:9]
	ds_write_b16_d16_hi v112, v42 offset:944
	v_mul_f32_e32 v40, v44, v85
	v_mul_f32_e32 v40, v40, v103
	v_bfe_u32 v41, v40, 16, 1
	v_add3_u32 v42, v40, v41, s87
	v_lshl_add_u64 v[40:41], v[56:57], 0, v[10:11]
	ds_write_b16_d16_hi v112, v42 offset:2304
	v_mul_f32_e32 v40, v45, v86
	v_mul_f32_e32 v40, v40, v103
	v_bfe_u32 v41, v40, 16, 1
	v_add3_u32 v42, v40, v41, s87
	v_lshl_add_u64 v[40:41], v[56:57], 0, v[12:13]
	ds_write_b16_d16_hi v112, v42 offset:2576
	v_mul_f32_e32 v40, v46, v87
	v_mul_f32_e32 v40, v40, v103
	v_bfe_u32 v41, v40, 16, 1
	v_add3_u32 v42, v40, v41, s87
	v_lshl_add_u64 v[40:41], v[56:57], 0, v[14:15]
	ds_write_b16_d16_hi v112, v42 offset:2848
	v_mul_f32_e32 v40, v47, v88
	v_mul_f32_e32 v40, v40, v103
	v_bfe_u32 v41, v40, 16, 1
	v_add3_u32 v42, v40, v41, s87
	v_lshl_add_u64 v[40:41], v[56:57], 0, v[16:17]
	ds_write_b16_d16_hi v112, v42 offset:3120
	v_mul_f32_e32 v40, v63, v89
	v_mul_f32_e32 v40, v40, v103
	v_bfe_u32 v41, v40, 16, 1
	v_add3_u32 v42, v40, v41, s87
	v_lshl_add_u64 v[40:41], v[56:57], 0, v[18:19]
	ds_write_b16_d16_hi v112, v42 offset:4480
	v_mul_f32_e32 v40, v65, v90
	v_mul_f32_e32 v40, v40, v103
	v_bfe_u32 v41, v40, 16, 1
	v_add3_u32 v42, v40, v41, s87
	v_lshl_add_u64 v[40:41], v[56:57], 0, v[20:21]
	ds_write_b16_d16_hi v112, v42 offset:4752
	v_mul_f32_e32 v40, v66, v91
	v_mul_f32_e32 v40, v40, v103
	v_bfe_u32 v41, v40, 16, 1
	v_add3_u32 v42, v40, v41, s87
	v_lshl_add_u64 v[40:41], v[56:57], 0, v[22:23]
	ds_write_b16_d16_hi v112, v42 offset:5024
	v_mul_f32_e32 v40, v67, v92
	v_mul_f32_e32 v40, v40, v103
	v_bfe_u32 v41, v40, 16, 1
	v_add3_u32 v42, v40, v41, s87
	v_lshl_add_u64 v[40:41], v[56:57], 0, v[24:25]
	ds_write_b16_d16_hi v112, v42 offset:5296
	v_mul_f32_e32 v40, v68, v93
	v_mul_f32_e32 v40, v40, v103
	v_bfe_u32 v41, v40, 16, 1
	v_add3_u32 v42, v40, v41, s87
	v_lshl_add_u64 v[40:41], v[56:57], 0, v[26:27]
	ds_write_b16_d16_hi v112, v42 offset:6656
	v_mul_f32_e32 v40, v69, v94
	v_mul_f32_e32 v40, v40, v103
	v_bfe_u32 v41, v40, 16, 1
	v_add3_u32 v42, v40, v41, s87
	v_lshl_add_u64 v[40:41], v[56:57], 0, v[28:29]
	ds_write_b16_d16_hi v112, v42 offset:6928
	v_mul_f32_e32 v40, v70, v95
	v_mul_f32_e32 v40, v40, v103
	v_bfe_u32 v41, v40, 16, 1
	v_add3_u32 v42, v40, v41, s87
	v_lshl_add_u64 v[40:41], v[56:57], 0, v[30:31]
	ds_write_b16_d16_hi v112, v42 offset:7200
	v_mul_f32_e32 v40, v71, v96
	v_mul_f32_e32 v40, v40, v103
	v_bfe_u32 v41, v40, 16, 1
	v_mul_f32_e32 v32, v32, v79
	v_add3_u32 v42, v40, v41, s87
	v_lshl_add_u64 v[40:41], v[56:57], 0, v[176:177]
	s_waitcnt vmcnt(0)
; __device__ __forceinline__ unsigned f2bf(float f) { unsigned u = __builtin_bit_cast(unsigned, f); return (u + 0x7fffu + ((u >> 16) & 1u)) >> 16; }
; __device__ __forceinline__ int crow(int r, int hi) { return (r & 3) + 8 * (r >> 2) + 4 * hi; }
; __device__ __forceinline__ void attn_unit(LAS unsigned char* lds, const bf16* Qh, const bf16* Kh, const bf16* VTh, const float* nrm, bf16* Y, const float* subln, float lam, int b, int h, int qb) {
;     ...
;         bf16* yb = Y + (tokb + qw0) * (size_t)D + h * 128 + r32;
; #pragma unroll
;         for (int blk = 0; blk < 4; ++blk) { const float g = subln[blk * 32 + r32];
; #pragma unroll
;             for (int r = 0; r < 16; ++r) yb[(size_t)crow(r, hi) * D + blk * 32] = (bf16)f2bf(o[blk][r] * ss[r] * g); }
	v_mul_f32_e32 v32, v32, v104
	ds_write_b16_d16_hi v112, v42 offset:7472
	v_bfe_u32 v40, v32, 16, 1
	v_add3_u32 v32, v32, v40, s87
	ds_write_b16_d16_hi v112, v32 offset:192
	v_mul_f32_e32 v2, v33, v81
	s_mov_b64 s[0:1], 0xc0
	v_mul_f32_e32 v2, v2, v104
	v_lshl_add_u64 v[0:1], v[0:1], 0, s[0:1]
	v_bfe_u32 v3, v2, 16, 1
	v_add3_u32 v32, v2, v3, s87
	v_lshl_add_u64 v[2:3], v[0:1], 0, v[4:5]
	ds_write_b16_d16_hi v112, v32 offset:464
	v_mul_f32_e32 v2, v34, v83
	v_mul_f32_e32 v2, v2, v104
	v_bfe_u32 v3, v2, 16, 1
	v_add3_u32 v4, v2, v3, s87
	v_lshl_add_u64 v[2:3], v[0:1], 0, v[6:7]
	ds_write_b16_d16_hi v112, v4 offset:736
	v_mul_f32_e32 v2, v35, v84
	v_mul_f32_e32 v2, v2, v104
	v_bfe_u32 v3, v2, 16, 1
	v_add3_u32 v4, v2, v3, s87
	v_lshl_add_u64 v[2:3], v[0:1], 0, v[8:9]
	ds_write_b16_d16_hi v112, v4 offset:1008
	v_mul_f32_e32 v2, v36, v85
	v_mul_f32_e32 v2, v2, v104
	v_bfe_u32 v3, v2, 16, 1
	v_add3_u32 v4, v2, v3, s87
	v_lshl_add_u64 v[2:3], v[0:1], 0, v[10:11]
	ds_write_b16_d16_hi v112, v4 offset:2368
	v_mul_f32_e32 v2, v37, v86
	v_mul_f32_e32 v2, v2, v104
	v_bfe_u32 v3, v2, 16, 1
	v_add3_u32 v4, v2, v3, s87
	v_lshl_add_u64 v[2:3], v[0:1], 0, v[12:13]
	ds_write_b16_d16_hi v112, v4 offset:2640
	v_mul_f32_e32 v2, v38, v87
	v_mul_f32_e32 v2, v2, v104
	v_bfe_u32 v3, v2, 16, 1
	v_add3_u32 v4, v2, v3, s87
	v_lshl_add_u64 v[2:3], v[0:1], 0, v[14:15]
	ds_write_b16_d16_hi v112, v4 offset:2912
	v_mul_f32_e32 v2, v39, v88
	v_mul_f32_e32 v2, v2, v104
	v_bfe_u32 v3, v2, 16, 1
	v_add3_u32 v4, v2, v3, s87
	v_lshl_add_u64 v[2:3], v[0:1], 0, v[16:17]
	ds_write_b16_d16_hi v112, v4 offset:3184
	v_mul_f32_e32 v2, v48, v89
	v_mul_f32_e32 v2, v2, v104
	v_bfe_u32 v3, v2, 16, 1
	v_add3_u32 v4, v2, v3, s87
	v_lshl_add_u64 v[2:3], v[0:1], 0, v[18:19]
	ds_write_b16_d16_hi v112, v4 offset:4544
	v_mul_f32_e32 v2, v49, v90
	v_mul_f32_e32 v2, v2, v104
	v_bfe_u32 v3, v2, 16, 1
	v_add3_u32 v4, v2, v3, s87
	v_lshl_add_u64 v[2:3], v[0:1], 0, v[20:21]
	ds_write_b16_d16_hi v112, v4 offset:4816
	v_mul_f32_e32 v2, v50, v91
	v_mul_f32_e32 v2, v2, v104
	v_bfe_u32 v3, v2, 16, 1
	v_add3_u32 v4, v2, v3, s87
	v_lshl_add_u64 v[2:3], v[0:1], 0, v[22:23]
	ds_write_b16_d16_hi v112, v4 offset:5088
	v_mul_f32_e32 v2, v51, v92
	v_mul_f32_e32 v2, v2, v104
	v_bfe_u32 v3, v2, 16, 1
	v_add3_u32 v4, v2, v3, s87
	v_lshl_add_u64 v[2:3], v[0:1], 0, v[24:25]
	ds_write_b16_d16_hi v112, v4 offset:5360
	v_mul_f32_e32 v2, v52, v93
	v_mul_f32_e32 v2, v2, v104
	v_bfe_u32 v3, v2, 16, 1
	v_add3_u32 v4, v2, v3, s87
	v_lshl_add_u64 v[2:3], v[0:1], 0, v[26:27]
	ds_write_b16_d16_hi v112, v4 offset:6720
	v_mul_f32_e32 v2, v53, v94
	v_mul_f32_e32 v2, v2, v104
	v_bfe_u32 v3, v2, 16, 1
	v_add3_u32 v4, v2, v3, s87
	v_lshl_add_u64 v[2:3], v[0:1], 0, v[28:29]
	ds_write_b16_d16_hi v112, v4 offset:6992
	v_mul_f32_e32 v2, v54, v95
	v_mul_f32_e32 v2, v2, v104
	v_bfe_u32 v3, v2, 16, 1
	v_add3_u32 v4, v2, v3, s87
	v_lshl_add_u64 v[2:3], v[0:1], 0, v[30:31]
	ds_write_b16_d16_hi v112, v4 offset:7264
	v_mul_f32_e32 v2, v64, v96
	v_mul_f32_e32 v2, v2, v104
	v_bfe_u32 v3, v2, 16, 1
	v_add3_u32 v2, v2, v3, s87
	v_lshl_add_u64 v[0:1], v[0:1], 0, v[176:177]
	ds_write_b16_d16_hi v112, v2 offset:7536
	s_waitcnt lgkmcnt(0)
	v_lshrrev_b32_e32 v55, 4, v203
	v_and_b32_e32 v42, 15, v203
	v_lshlrev_b32_e32 v42, 4, v42
	v_lshl_add_u32 v40, v55, 12, v42
	v_lshl_add_u32 v41, v55, 8, v42
	v_lshl_add_u32 v41, v55, 4, v41
	v_mov_b32_e32 v55, s81
	v_lshlrev_b32_e32 v55, 8, v55
	v_and_b32_e32 v55, 0xc000, v55
	v_add_u32_e32 v41, v55, v41
	ds_read_b128 v[0:3], v41
	ds_read_b128 v[4:7], v41 offset:1088
	ds_read_b128 v[8:11], v41 offset:2176
	ds_read_b128 v[12:15], v41 offset:3264
	ds_read_b128 v[16:19], v41 offset:4352
	ds_read_b128 v[20:23], v41 offset:5440
	ds_read_b128 v[24:27], v41 offset:6528
	ds_read_b128 v[28:31], v41 offset:7616
	v_add_u32_e32 v42, 0x4000, v40
	v_add_u32_e32 v55, 0x8000, v40
	v_add_u32_e32 v56, 0xc000, v40
	v_add_u32_e32 v57, 0x10000, v40
	v_add_u32_e32 v82, 0x14000, v40
	v_add_u32_e32 v97, 0x18000, v40
	v_add_u32_e32 v100, 0x1c000, v40
	s_nop 1
	s_waitcnt lgkmcnt(7)
	global_store_dwordx4 v40, v[0:3], s[98:99]
	s_waitcnt lgkmcnt(6)
	global_store_dwordx4 v42, v[4:7], s[98:99]
	s_waitcnt lgkmcnt(5)
	global_store_dwordx4 v55, v[8:11], s[98:99]
	s_waitcnt lgkmcnt(4)
	global_store_dwordx4 v56, v[12:15], s[98:99]
	s_waitcnt lgkmcnt(3)
	global_store_dwordx4 v57, v[16:19], s[98:99]
	s_waitcnt lgkmcnt(2)
	global_store_dwordx4 v82, v[20:23], s[98:99]
	s_waitcnt lgkmcnt(1)
	global_store_dwordx4 v97, v[24:27], s[98:99]
	s_waitcnt lgkmcnt(0)
	global_store_dwordx4 v100, v[28:31], s[98:99]
	s_branch .LBB0_876
